# chain: two rendezvous per step (decay+PD pieces first, VT pieces second) so the next step's LDS-DMA is issued while this step's VT pieces are still landing; plus scalar-base DMA issue and o stores
# baseline (speedup 1.0000x reference)
; #define LAS __attribute__((address_space(3)))
; #define RD_QD(dst, s0) _Pragma("unroll") for (int s_ = 0; s_ < 4; ++s_) { dst[s_] = *(const LAS bf16x8*)(B + CH_QD + i0 * 256 + (((2 * ((s0) + s_) + hi) ^ (i0 & 15)) << 4)); \
;                 dst[4 + s_] = *(const LAS bf16x8*)(B + CH_QD + i1 * 256 + (((2 * ((s0) + s_) + hi) ^ (i1 & 15)) << 4)); }
; #define RD_KT(dst, db0) _Pragma("unroll") for (int q_ = 0; q_ < 2; ++q_) { const int d_ = ((db0) + q_) * 32 + r32; \
;                 _Pragma("unroll") for (int ks_ = 0; ks_ < 4; ++ks_) dst[q_ * 4 + ks_] = *(const LAS bf16x8*)(B + CH_KT + d_ * 128 + (((2 * ks_ + hi) ^ ((d_ >> 1) & 7)) << 4)); }
; #define DECAY(db_) do { f32x4 dc_[4]; _Pragma("unroll") for (int a4_ = 0; a4_ < 4; ++a4_) dc_[a4_] = *(const LAS f32x4*)(B + CH_DEC + ((db_) * 32 + 8 * a4_ + 4 * hi) * 4); \
;                 _Pragma("unroll") for (int a4_ = 0; a4_ < 4; ++a4_) _Pragma("unroll") for (int b4_ = 0; b4_ < 4; ++b4_) T[db_][a4_ * 4 + b4_] *= dc_[a4_][b4_]; } while (0)
; DI void phase_gla_chain(const Params& P, int l, int task0, int ntask_stride, LAS unsigned char* lds) {
;     ...
;             const int i0 = r32, i1 = 32 + r32; const int vv = wid * 32 + r32;
;             bf16x8 fa[8], fb[8], vf[4];
;             f32x16 o[2]; for (int x = 0; x < 16; ++x) { o[0][x] = 0.f; o[1][x] = 0.f; }
;     ...
;             RD_QD(fa, 0);
; #pragma unroll
;             for (int ks = 0; ks < 4; ++ks) vf[ks] = *(const LAS bf16x8*)(B + CH_VT + vv * 128 + (((2 * ks + hi) ^ ((vv >> 1) & 7)) << 4));
;             __builtin_amdgcn_sched_barrier(0);
;             RD_QD(fb, 4);
;             __builtin_amdgcn_sched_barrier(0);
;             MM_QD(fa, 0);
;             DECAY(0); DECAY(1);
;             __builtin_amdgcn_sched_barrier(0);
; #pragma unroll
;             for (int ks = 0; ks < 4; ++ks) { fa[ks] = *(const LAS bf16x8*)(B + CH_AM + i0 * 128 + (((2 * ks + hi) ^ ((i0 >> 1) & 7)) << 4)); fa[4 + ks] = *(const LAS bf16x8*)(B + CH_AM + i1 * 128 + (((2 * ks + hi) ^ ((i1 >> 1) & 7)) << 4)); }
;             __builtin_amdgcn_sched_barrier(0);
;             MM_QD(fb, 4);
;             DECAY(2); DECAY(3);
;             __builtin_amdgcn_sched_barrier(0);
;             RD_KT(fb, 0);
.LBB0_409:
	s_mul_i32 s92, s92, 0x12400
	s_add_i32 s22, s92, 0
	v_add_u32_e32 v74, s22, v205
	v_add_u32_e32 v75, s22, v141
	v_add_u32_e32 v66, v74, v149
	v_add_u32_e32 v70, v75, v149
	v_add_u32_e32 v76, v74, v151
	ds_read_b128 v[66:69], v66
	ds_read_b128 v[70:73], v70
	v_add_u32_e32 v77, v75, v151
	ds_read_b128 v[182:185], v76
	ds_read_b128 v[186:189], v77
	v_add_u32_e32 v76, v74, v153
	v_add_u32_e32 v77, v75, v153
	ds_read_b128 v[190:193], v76
	ds_read_b128 v[194:197], v77
	v_add_u32_e32 v76, v74, v160
	v_add_u32_e32 v77, v75, v160
	ds_read_b128 v[198:201], v76
	ds_read_b128 v[208:211], v77
	v_add_u32_e32 v76, v74, v167
	v_add_u32_e32 v77, v75, v167
	ds_read_b128 v[212:215], v76
	ds_read_b128 v[216:219], v77
	v_add_u32_e32 v76, v74, v168
	v_add_u32_e32 v77, v75, v168
	ds_read_b128 v[220:223], v76
	ds_read_b128 v[130:133], v77
	v_add_u32_e32 v76, v74, v169
	v_add_u32_e32 v74, v74, v170
	v_add_u32_e32 v77, v75, v169
	ds_read_b128 v[126:129], v76
	ds_read_b128 v[122:125], v77
	v_add_u32_e32 v75, v75, v170
	ds_read_b128 v[118:121], v74
	ds_read_b128 v[114:117], v75
	v_cvt_pk_bf16_f32 v74, v2, v3
	v_cvt_pk_bf16_f32 v75, v4, v5
	v_cvt_pk_bf16_f32 v76, v6, v7
	v_cvt_pk_bf16_f32 v77, v8, v9
	v_cvt_pk_bf16_f32 v224, v10, v11
	v_cvt_pk_bf16_f32 v225, v12, v13
	s_waitcnt lgkmcnt(0)
	v_mfma_f32_32x32x16_bf16 v[82:97], v[66:69], v[74:77], 0
	v_cvt_pk_bf16_f32 v226, v14, v15
	v_cvt_pk_bf16_f32 v227, v16, v17
	v_add_u32_e32 v207, s22, v146
	v_add_u32_e32 v231, 0x12000, v207
	v_cvt_pk_bf16_f32 v228, v26, v27
	v_cvt_pk_bf16_f32 v229, v28, v29
	v_cvt_pk_bf16_f32 v230, v30, v31
	v_mfma_f32_32x32x16_bf16 v[66:81], v[70:73], v[74:77], 0
	v_mfma_f32_32x32x16_bf16 v[82:97], v[182:185], v[224:227], v[82:97]
	v_cvt_pk_bf16_f32 v182, v18, v19
	v_cvt_pk_bf16_f32 v183, v20, v21
	v_cvt_pk_bf16_f32 v184, v22, v23
	v_cvt_pk_bf16_f32 v185, v24, v25
	v_mfma_f32_32x32x16_bf16 v[66:81], v[186:189], v[224:227], v[66:81]
	ds_read_b128 v[186:189], v231 offset:64
	ds_read_b128 v[224:227], v231 offset:96
	ds_read_b128 v[232:235], v231
	ds_read_b128 v[236:239], v231 offset:32
	v_cvt_pk_bf16_f32 v231, v32, v33
	s_waitcnt lgkmcnt(0)
	v_pk_mul_f32 v[10:11], v[10:11], v[186:187]
	v_pk_mul_f32 v[12:13], v[12:13], v[188:189]
	v_pk_mul_f32 v[14:15], v[14:15], v[224:225]
	v_pk_mul_f32 v[6:7], v[6:7], v[236:237]
	v_pk_mul_f32 v[16:17], v[16:17], v[226:227]
	v_mfma_f32_32x32x16_bf16 v[82:97], v[190:193], v[182:185], v[82:97]
	v_mul_f32_e64 v8, v8, v238
	v_mul_f32_e64 v9, v9, v239
	v_mul_f32_e64 v4, v4, v234
	v_mul_f32_e64 v5, v5, v235
	v_mul_f32_e64 v2, v2, v232
	v_mul_f32_e64 v3, v3, v233
	v_mfma_f32_32x32x16_bf16 v[66:81], v[194:197], v[182:185], v[66:81]
	v_add_u32_e32 v194, 0x12080, v207
	ds_read_b128 v[182:185], v194 offset:64
	ds_read_b128 v[186:189], v194 offset:96
	ds_read_b128 v[190:193], v194
	ds_read_b128 v[194:197], v194 offset:32
	s_waitcnt lgkmcnt(0)
	v_pk_mul_f32 v[26:27], v[26:27], v[182:183]
	v_pk_mul_f32 v[30:31], v[30:31], v[186:187]
	v_pk_mul_f32 v[32:33], v[32:33], v[188:189]
	v_pk_mul_f32 v[22:23], v[22:23], v[194:195]
	v_pk_mul_f32 v[28:29], v[28:29], v[184:185]
	v_pk_mul_f32 v[24:25], v[24:25], v[196:197]
	v_pk_mul_f32 v[20:21], v[20:21], v[192:193]
	v_pk_mul_f32 v[18:19], v[18:19], v[190:191]
	v_mfma_f32_32x32x16_bf16 v[82:97], v[198:201], v[228:231], v[82:97]
	v_mfma_f32_32x32x16_bf16 v[66:81], v[208:211], v[228:231], v[66:81]
	v_add_u32_e32 v224, s22, v143
	v_add_u32_e32 v225, s22, v145
	v_add_u32_e32 v240, v224, v162
	v_add_u32_e32 v186, v225, v162
	v_add_u32_e32 v241, v224, v164
	v_add_u32_e32 v194, v225, v164
	v_add_u32_e32 v242, v224, v165
	v_add_u32_e32 v208, v225, v165
	v_add_u32_e32 v243, v224, v166
	v_add_u32_e32 v228, v225, v166
	ds_read_b128 v[182:185], v240 offset:16384
	ds_read_b128 v[186:189], v186 offset:16384
	ds_read_b128 v[190:193], v241 offset:16384
	ds_read_b128 v[194:197], v194 offset:16384
	ds_read_b128 v[198:201], v242 offset:16384
	ds_read_b128 v[208:211], v208 offset:16384
	ds_read_b128 v[224:227], v243 offset:16384
	ds_read_b128 v[228:231], v228 offset:16384
	v_cvt_pk_bf16_f32 v232, v34, v35
	v_cvt_pk_bf16_f32 v233, v36, v37
	v_cvt_pk_bf16_f32 v234, v38, v39
	v_cvt_pk_bf16_f32 v235, v40, v41
	s_nop 1
	v_mfma_f32_32x32x16_bf16 v[82:97], v[212:215], v[232:235], v[82:97]
	v_cvt_pk_bf16_f32 v212, v42, v43
	v_cvt_pk_bf16_f32 v213, v44, v45
	v_cvt_pk_bf16_f32 v214, v46, v47
	v_cvt_pk_bf16_f32 v215, v48, v49
	v_mfma_f32_32x32x16_bf16 v[66:81], v[216:219], v[232:235], v[66:81]
	v_cvt_pk_bf16_f32 v216, v50, v51
	v_cvt_pk_bf16_f32 v217, v52, v53
	v_cvt_pk_bf16_f32 v218, v54, v55
	v_cvt_pk_bf16_f32 v219, v56, v57
	v_mfma_f32_32x32x16_bf16 v[82:97], v[220:223], v[212:215], v[82:97]
	v_add_u32_e32 v223, 0x12100, v207
	v_add_u32_e32 v207, 0x12180, v207
	v_cvt_pk_bf16_f32 v220, v58, v59
	v_cvt_pk_bf16_f32 v221, v60, v61
	v_cvt_pk_bf16_f32 v222, v62, v63
	v_mfma_f32_32x32x16_bf16 v[66:81], v[130:133], v[212:215], v[66:81]
	ds_read_b128 v[130:133], v223 offset:64
	ds_read_b128 v[212:215], v223 offset:96
	ds_read_b128 v[232:235], v223
	ds_read_b128 v[236:239], v223 offset:32
	v_cvt_pk_bf16_f32 v223, v64, v65
	s_waitcnt lgkmcnt(0)
	v_pk_mul_f32 v[42:43], v[42:43], v[130:131]
	v_pk_mul_f32 v[46:47], v[46:47], v[212:213]
	v_pk_mul_f32 v[48:49], v[48:49], v[214:215]
	v_pk_mul_f32 v[44:45], v[44:45], v[132:133]
	v_pk_mul_f32 v[38:39], v[38:39], v[236:237]
	v_mfma_f32_32x32x16_bf16 v[82:97], v[126:129], v[216:219], v[82:97]
	v_mul_f32_e64 v40, v40, v238
	v_mul_f32_e64 v41, v41, v239
	v_mul_f32_e64 v36, v36, v234
	v_mul_f32_e64 v37, v37, v235
	v_mul_f32_e64 v34, v34, v232
	v_mul_f32_e64 v35, v35, v233
	v_mfma_f32_32x32x16_bf16 v[66:81], v[122:125], v[216:219], v[66:81]
	ds_read_b128 v[122:125], v207 offset:64
	ds_read_b128 v[126:129], v207 offset:96
	ds_read_b128 v[130:133], v207
	ds_read_b128 v[212:215], v207 offset:32
	s_waitcnt lgkmcnt(0)
	v_pk_mul_f32 v[58:59], v[58:59], v[122:123]
	v_pk_mul_f32 v[62:63], v[62:63], v[126:127]
	v_pk_mul_f32 v[64:65], v[64:65], v[128:129]
	v_pk_mul_f32 v[54:55], v[54:55], v[212:213]
	v_pk_mul_f32 v[60:61], v[60:61], v[124:125]
	v_pk_mul_f32 v[56:57], v[56:57], v[214:215]
	v_pk_mul_f32 v[52:53], v[52:53], v[132:133]
	v_pk_mul_f32 v[50:51], v[50:51], v[130:131]
	v_mfma_f32_32x32x16_bf16 v[82:97], v[118:121], v[220:223], v[82:97]
	v_mfma_f32_32x32x16_bf16 v[66:81], v[114:117], v[220:223], v[66:81]
	ds_read_b128 v[114:117], v240 offset:24576
	ds_read_b128 v[118:121], v240 offset:28672
	ds_read_b128 v[122:125], v241 offset:24576
	ds_read_b128 v[126:129], v241 offset:28672
	ds_read_b128 v[130:133], v242 offset:24576
	ds_read_b128 v[212:215], v242 offset:28672
	ds_read_b128 v[216:219], v243 offset:24576
	ds_read_b128 v[220:223], v243 offset:28672
	s_waitcnt vmcnt(25)
	s_barrier
; #define LAS __attribute__((address_space(3)))
; DI int crow(int r, int hi) { return (r & 3) + 8 * (r >> 2) + 4 * hi; }
; DI unsigned pkbf(float a, float b) { f32x2 v = {a, b}; bfx2 r = __builtin_convertvector(v, bfx2); return __builtin_bit_cast(unsigned, r); }
; #define RD_KT(dst, db0) _Pragma("unroll") for (int q_ = 0; q_ < 2; ++q_) { const int d_ = ((db0) + q_) * 32 + r32; \
;                 _Pragma("unroll") for (int ks_ = 0; ks_ < 4; ++ks_) dst[q_ * 4 + ks_] = *(const LAS bf16x8*)(B + CH_KT + d_ * 128 + (((2 * ks_ + hi) ^ ((d_ >> 1) & 7)) << 4)); }
; #define MM_KT(src, db0) _Pragma("unroll") for (int q_ = 0; q_ < 2; ++q_) { \
;                 _Pragma("unroll") for (int ks_ = 0; ks_ < 4; ++ks_) T[(db0) + q_] = __builtin_amdgcn_mfma_f32_32x32x16_bf16(src[q_ * 4 + ks_], vf[ks_], T[(db0) + q_], 0, 0, 0); }
; DI void phase_gla_chain(const Params& P, int l, int task0, int ntask_stride, LAS unsigned char* lds) {
;     ...
;             for (int ks = 0; ks < 4; ++ks) vf[ks] = *(const LAS bf16x8*)(B + CH_VT + vv * 128 + (((2 * ks + hi) ^ ((vv >> 1) & 7)) << 4));
;     ...
; #pragma unroll
;             for (int ks = 0; ks < 4; ++ks) { o[0] = __builtin_amdgcn_mfma_f32_32x32x16_bf16(fa[ks], vf[ks], o[0], 0, 0, 0); o[1] = __builtin_amdgcn_mfma_f32_32x32x16_bf16(fa[4 + ks], vf[ks], o[1], 0, 0, 0); }
;             __builtin_amdgcn_sched_barrier(0);
;             RD_KT(fa, 2);
;             __builtin_amdgcn_sched_barrier(0);
;             MM_KT(fb, 0);
;             __builtin_amdgcn_sched_barrier(0);
;             MM_KT(fa, 2);
;     ...
;             { const int cs = dir ? 63 - n : n; const size_t tokb = (size_t)sq * SEQL + cs * 64; const int odd = lane & 1;
;               bf16_t* ob = OFB + (size_t)dir * MTOK * 1024 + h * 256 + wid * 32 + (r32 & ~1);
; #pragma unroll
;               for (int ib = 0; ib < 2; ++ib)
; #pragma unroll
;                   for (int x = 0; x < 16; x += 2) { float ea_ = o[ib][x], eb_ = o[ib][x + 1]; asm volatile("" : "+v"(ea_), "+v"(eb_)); const float mine = odd ? eb_ : ea_, give = odd ? ea_ : eb_;
;                       const float got = __int_as_float(__builtin_amdgcn_update_dpp(0, __float_as_int(give), 0xB1, 0xF, 0xF, true));
;                       const unsigned w = odd ? pkbf(got, mine) : pkbf(mine, got);
;                       *(unsigned*)(ob + (tokb + ib * 32 + crow(x + odd, hi)) * 1024) = w; } }
	v_add_u32_e32 v249, s22, v173
	v_add_u32_e32 v250, v249, v162
	v_add_u32_e32 v251, v249, v164
	ds_read_b128 v[110:113], v250 offset:40960
	ds_read_b128 v[106:109], v251 offset:40960
	v_add_u32_e32 v250, v249, v165
	v_add_u32_e32 v249, v249, v166
	ds_read_b128 v[102:105], v250 offset:40960
	ds_read_b128 v[98:101], v249 offset:40960
	s_waitcnt lgkmcnt(0)
	v_mfma_f32_32x32x16_bf16 v[82:97], v[182:185], v[110:113], v[82:97]
	v_mfma_f32_32x32x16_bf16 v[66:81], v[186:189], v[110:113], v[66:81]
	v_mfma_f32_32x32x16_bf16 v[82:97], v[190:193], v[106:109], v[82:97]
	v_mfma_f32_32x32x16_bf16 v[66:81], v[194:197], v[106:109], v[66:81]
	v_mfma_f32_32x32x16_bf16 v[82:97], v[198:201], v[102:105], v[82:97]
	v_mfma_f32_32x32x16_bf16 v[66:81], v[208:211], v[102:105], v[66:81]
	v_mfma_f32_32x32x16_bf16 v[82:97], v[224:227], v[98:101], v[82:97]
	v_mfma_f32_32x32x16_bf16 v[66:81], v[228:231], v[98:101], v[66:81]
	ds_read_b128 v[182:185], v240 offset:32768
	ds_read_b128 v[186:189], v240 offset:36864
	ds_read_b128 v[190:193], v241 offset:32768
	ds_read_b128 v[194:197], v241 offset:36864
	ds_read_b128 v[198:201], v242 offset:32768
	ds_read_b128 v[208:211], v242 offset:36864
	ds_read_b128 v[224:227], v243 offset:32768
	ds_read_b128 v[228:231], v243 offset:36864
	s_waitcnt lgkmcnt(0)
	v_mfma_f32_32x32x16_bf16 v[2:17], v[114:117], v[110:113], v[2:17]
	v_mfma_f32_32x32x16_bf16 v[18:33], v[118:121], v[110:113], v[18:33]
	v_mfma_f32_32x32x16_bf16 v[2:17], v[122:125], v[106:109], v[2:17]
	v_mfma_f32_32x32x16_bf16 v[18:33], v[126:129], v[106:109], v[18:33]
	v_mfma_f32_32x32x16_bf16 v[2:17], v[130:133], v[102:105], v[2:17]
	v_mfma_f32_32x32x16_bf16 v[18:33], v[212:215], v[102:105], v[18:33]
	v_mfma_f32_32x32x16_bf16 v[2:17], v[216:219], v[98:101], v[2:17]
	v_mfma_f32_32x32x16_bf16 v[18:33], v[220:223], v[98:101], v[18:33]
	s_add_i32 s64, s8, 1
	s_and_b64 s[22:23], s[10:11], exec
	s_cselect_b32 s22, s91, s64
	s_lshl_b32 s22, s22, 6
	s_add_u32 s23, s20, s22
	v_cndmask_b32_e64 v114, v82, v83, s[0:1]
	s_addc_u32 s22, s21, 0
	v_mfma_f32_32x32x16_bf16 v[34:49], v[182:185], v[110:113], v[34:49]
	v_mov_b32_dpp v114, v114 quad_perm:[1,0,3,2] row_mask:0xf bank_mask:0xf bound_ctrl:1
	v_cndmask_b32_e64 v83, v83, v114, s[0:1]
	v_cndmask_b32_e64 v82, v114, v82, s[0:1]
	v_cvt_pk_bf16_f32 v114, v82, v83
	v_readfirstlane_b32 s98, v158
	v_readfirstlane_b32 s99, v159
	v_and_b32_e32 v244, 30, v137
	v_lshlrev_b32_e32 v244, 1, v244
	v_lshl_add_u32 v244, v136, 11, v244
	s_lshl_b32 s100, s23, 11
	s_add_u32 s98, s98, s100
	s_addc_u32 s99, s99, 0
	s_add_u32 s100, s98, 0x800
	s_addc_u32 s101, s99, 0
	global_store_dword v244, v114, s[100:101] offset:-2048
	v_mov_b32_e32 v82, v84
	v_mfma_f32_32x32x16_bf16 v[50:65], v[186:189], v[110:113], v[50:65]
	v_cndmask_b32_e64 v83, v82, v85, s[0:1]
	s_add_i32 s8, s8, -1
	s_add_i32 s90, s90, 1
	v_mov_b32_dpp v83, v83 quad_perm:[1,0,3,2] row_mask:0xf bank_mask:0xf bound_ctrl:1
	v_cndmask_b32_e64 v84, v85, v83, s[0:1]
	v_cndmask_b32_e64 v82, v83, v82, s[0:1]
	v_cvt_pk_bf16_f32 v84, v82, v84
	global_store_dword v244, v84, s[100:101] offset:2048
	v_mov_b32_e32 v82, v87
	v_mfma_f32_32x32x16_bf16 v[34:49], v[190:193], v[106:109], v[34:49]
	v_cndmask_b32_e64 v83, v86, v82, s[0:1]
	s_nop 1
	v_mov_b32_dpp v83, v83 quad_perm:[1,0,3,2] row_mask:0xf bank_mask:0xf bound_ctrl:1
	v_cndmask_b32_e64 v82, v82, v83, s[0:1]
	v_cndmask_b32_e64 v83, v83, v86, s[0:1]
	v_cvt_pk_bf16_f32 v84, v83, v82
	s_add_u32 s100, s98, 0x4800
	s_addc_u32 s101, s99, 0
	global_store_dword v244, v84, s[100:101] offset:-2048
	v_mov_b32_e32 v82, v88
	v_mfma_f32_32x32x16_bf16 v[50:65], v[194:197], v[106:109], v[50:65]
	v_cndmask_b32_e64 v83, v82, v89, s[0:1]
	s_nop 1
	v_mov_b32_dpp v83, v83 quad_perm:[1,0,3,2] row_mask:0xf bank_mask:0xf bound_ctrl:1
	v_cndmask_b32_e64 v84, v89, v83, s[0:1]
	v_cndmask_b32_e64 v82, v83, v82, s[0:1]
	v_cvt_pk_bf16_f32 v84, v82, v84
	global_store_dword v244, v84, s[100:101] offset:2048
	v_mov_b32_e32 v82, v90
	v_mfma_f32_32x32x16_bf16 v[34:49], v[198:201], v[102:105], v[34:49]
	v_cndmask_b32_e64 v83, v82, v91, s[0:1]
	s_nop 1
	v_mov_b32_dpp v83, v83 quad_perm:[1,0,3,2] row_mask:0xf bank_mask:0xf bound_ctrl:1
	v_cndmask_b32_e64 v84, v91, v83, s[0:1]
	v_cndmask_b32_e64 v82, v83, v82, s[0:1]
	v_cvt_pk_bf16_f32 v84, v82, v84
	s_add_u32 s100, s98, 0x8800
	s_addc_u32 s101, s99, 0
	global_store_dword v244, v84, s[100:101] offset:-2048
	v_mov_b32_e32 v82, v93
	v_mfma_f32_32x32x16_bf16 v[50:65], v[208:211], v[102:105], v[50:65]
	v_cndmask_b32_e64 v83, v92, v82, s[0:1]
	s_nop 1
	v_mov_b32_dpp v83, v83 quad_perm:[1,0,3,2] row_mask:0xf bank_mask:0xf bound_ctrl:1
	v_cndmask_b32_e64 v82, v82, v83, s[0:1]
	v_cndmask_b32_e64 v83, v83, v92, s[0:1]
	v_cvt_pk_bf16_f32 v84, v83, v82
	global_store_dword v244, v84, s[100:101] offset:2048
	v_mov_b32_e32 v82, v94
	v_mfma_f32_32x32x16_bf16 v[34:49], v[224:227], v[98:101], v[34:49]
	v_cndmask_b32_e64 v83, v82, v95, s[0:1]
	s_nop 1
	v_mov_b32_dpp v83, v83 quad_perm:[1,0,3,2] row_mask:0xf bank_mask:0xf bound_ctrl:1
	v_cndmask_b32_e64 v84, v95, v83, s[0:1]
	v_cndmask_b32_e64 v82, v83, v82, s[0:1]
	v_cvt_pk_bf16_f32 v84, v82, v84
	s_add_u32 s100, s98, 0xc800
	s_addc_u32 s101, s99, 0
	global_store_dword v244, v84, s[100:101] offset:-2048
	v_mov_b32_e32 v82, v96
	v_mfma_f32_32x32x16_bf16 v[50:65], v[228:231], v[98:101], v[50:65]
	v_cndmask_b32_e64 v83, v82, v97, s[0:1]
	s_nop 1
; DI int crow(int r, int hi) { return (r & 3) + 8 * (r >> 2) + 4 * hi; }
; DI unsigned pkbf(float a, float b) { f32x2 v = {a, b}; bfx2 r = __builtin_convertvector(v, bfx2); return __builtin_bit_cast(unsigned, r); }
; DI void phase_gla_chain(const Params& P, int l, int task0, int ntask_stride, LAS unsigned char* lds) {
;     ...
;         __syncthreads();
;         CH_ISSUE(0, 0);
;         for (int n = 0; n < 64; ++n) {
;             const int b = n & 1;
;             if (n == 0) asm volatile("s_waitcnt vmcnt(0)" ::: "memory"); else asm volatile("s_waitcnt vmcnt(16)" ::: "memory");
;             __builtin_amdgcn_s_barrier();
;             asm volatile("" ::: "memory");
;             if (n + 1 < 64) CH_ISSUE(n + 1, b ^ 1);
;     ...
;             { const int cs = dir ? 63 - n : n; const size_t tokb = (size_t)sq * SEQL + cs * 64; const int odd = lane & 1;
;               bf16_t* ob = OFB + (size_t)dir * MTOK * 1024 + h * 256 + wid * 32 + (r32 & ~1);
; #pragma unroll
;               for (int ib = 0; ib < 2; ++ib)
; #pragma unroll
;                   for (int x = 0; x < 16; x += 2) { float ea_ = o[ib][x], eb_ = o[ib][x + 1]; asm volatile("" : "+v"(ea_), "+v"(eb_)); const float mine = odd ? eb_ : ea_, give = odd ? ea_ : eb_;
;                       const float got = __int_as_float(__builtin_amdgcn_update_dpp(0, __float_as_int(give), 0xB1, 0xF, 0xF, true));
;                       const unsigned w = odd ? pkbf(got, mine) : pkbf(mine, got);
;                       *(unsigned*)(ob + (tokb + ib * 32 + crow(x + odd, hi)) * 1024) = w; } }
	v_mov_b32_dpp v83, v83 quad_perm:[1,0,3,2] row_mask:0xf bank_mask:0xf bound_ctrl:1
	v_cndmask_b32_e64 v84, v97, v83, s[0:1]
	v_cndmask_b32_e64 v82, v83, v82, s[0:1]
	v_cvt_pk_bf16_f32 v84, v82, v84
	global_store_dword v244, v84, s[100:101] offset:2048
	s_or_b32 s23, s23, 32
	v_cndmask_b32_e64 v82, v66, v67, s[0:1]
	s_nop 0
	v_mov_b32_dpp v82, v82 quad_perm:[1,0,3,2] row_mask:0xf bank_mask:0xf bound_ctrl:1
	v_cndmask_b32_e64 v67, v67, v82, s[0:1]
	v_cndmask_b32_e64 v66, v82, v66, s[0:1]
	v_cvt_pk_bf16_f32 v82, v66, v67
	s_add_u32 s100, s98, 0x10800
	s_addc_u32 s101, s99, 0
	global_store_dword v244, v82, s[100:101] offset:-2048
	v_mov_b32_e32 v66, v68
	s_nop 0
	v_cndmask_b32_e64 v67, v66, v69, s[0:1]
	s_nop 1
	v_mov_b32_dpp v67, v67 quad_perm:[1,0,3,2] row_mask:0xf bank_mask:0xf bound_ctrl:1
	v_cndmask_b32_e64 v68, v69, v67, s[0:1]
	v_cndmask_b32_e64 v66, v67, v66, s[0:1]
	v_cvt_pk_bf16_f32 v68, v66, v68
	global_store_dword v244, v68, s[100:101] offset:2048
	v_mov_b32_e32 v66, v70
	s_nop 0
	v_cndmask_b32_e64 v67, v66, v71, s[0:1]
	s_nop 1
	v_mov_b32_dpp v67, v67 quad_perm:[1,0,3,2] row_mask:0xf bank_mask:0xf bound_ctrl:1
	v_cndmask_b32_e64 v68, v71, v67, s[0:1]
	v_cndmask_b32_e64 v66, v67, v66, s[0:1]
	v_cvt_pk_bf16_f32 v68, v66, v68
	s_add_u32 s100, s98, 0x14800
	s_addc_u32 s101, s99, 0
	global_store_dword v244, v68, s[100:101] offset:-2048
	v_mov_b32_e32 v66, v73
	s_nop 0
	v_cndmask_b32_e64 v67, v72, v66, s[0:1]
	s_nop 1
	v_mov_b32_dpp v67, v67 quad_perm:[1,0,3,2] row_mask:0xf bank_mask:0xf bound_ctrl:1
	v_cndmask_b32_e64 v66, v66, v67, s[0:1]
	v_cndmask_b32_e64 v67, v67, v72, s[0:1]
	v_cvt_pk_bf16_f32 v68, v67, v66
	global_store_dword v244, v68, s[100:101] offset:2048
	v_mov_b32_e32 v66, v74
	s_nop 0
	v_cndmask_b32_e64 v67, v66, v75, s[0:1]
	s_nop 1
	v_mov_b32_dpp v67, v67 quad_perm:[1,0,3,2] row_mask:0xf bank_mask:0xf bound_ctrl:1
	v_cndmask_b32_e64 v68, v75, v67, s[0:1]
	v_cndmask_b32_e64 v66, v67, v66, s[0:1]
	v_cvt_pk_bf16_f32 v68, v66, v68
	s_add_u32 s100, s98, 0x18800
	s_addc_u32 s101, s99, 0
	global_store_dword v244, v68, s[100:101] offset:-2048
	v_mov_b32_e32 v66, v76
	s_nop 0
	v_cndmask_b32_e64 v67, v66, v77, s[0:1]
	s_nop 1
	v_mov_b32_dpp v67, v67 quad_perm:[1,0,3,2] row_mask:0xf bank_mask:0xf bound_ctrl:1
	v_cndmask_b32_e64 v68, v77, v67, s[0:1]
	v_cndmask_b32_e64 v66, v67, v66, s[0:1]
	v_cvt_pk_bf16_f32 v68, v66, v68
	global_store_dword v244, v68, s[100:101] offset:2048
	v_mov_b32_e32 v66, v79
	s_nop 0
	v_cndmask_b32_e64 v67, v78, v66, s[0:1]
	s_nop 1
	v_mov_b32_dpp v67, v67 quad_perm:[1,0,3,2] row_mask:0xf bank_mask:0xf bound_ctrl:1
	v_cndmask_b32_e64 v66, v66, v67, s[0:1]
	v_cndmask_b32_e64 v67, v67, v78, s[0:1]
	v_cvt_pk_bf16_f32 v68, v67, v66
	s_add_u32 s100, s98, 0x1c800
	s_addc_u32 s101, s99, 0
	global_store_dword v244, v68, s[100:101] offset:-2048
	v_mov_b32_e32 v66, v81
	s_nop 0
	v_cndmask_b32_e64 v67, v80, v66, s[0:1]
	s_nop 1
	v_mov_b32_dpp v67, v67 quad_perm:[1,0,3,2] row_mask:0xf bank_mask:0xf bound_ctrl:1
	v_cndmask_b32_e64 v66, v66, v67, s[0:1]
	v_cndmask_b32_e64 v67, v67, v80, s[0:1]
	v_cvt_pk_bf16_f32 v68, v67, v66
	global_store_dword v244, v68, s[100:101] offset:2048
	s_cmp_eq_u32 s8, -2
	s_cbranch_scc1 .LBB0_403
.LBB0_410:
	s_add_i32 s91, s90, -1
	s_cmp_lg_u32 s91, 1
	s_cbranch_scc1 .Lchain_w_0
	s_waitcnt vmcnt(16)
.Lchain_w_0:
	s_waitcnt vmcnt(20)
	s_barrier
	s_and_b32 s92, s91, 1
	s_cmp_eq_u32 s8, -1
	s_cbranch_scc1 .Lchain_last_0
	s_and_b64 s[22:23], s[10:11], exec
	s_cselect_b32 s22, s90, s8
	s_add_i32 s22, s22, s89
	s_lshl_b32 s22, s22, 2
	s_or_b32 s96, s22, s88
	s_ashr_i32 s97, s96, 31
	s_add_u32 s22, s25, s96
	s_addc_u32 s23, 0, s97
	s_mul_i32 s93, s23, 0xa000
	s_mul_hi_u32 vcc_lo, s22, 0xa000
	s_add_i32 vcc_lo, vcc_lo, s93
	s_mul_i32 s93, s22, 0xa000
	s_add_u32 vcc_hi, s27, s93
	s_addc_u32 vcc_lo, s28, vcc_lo
	s_lshl_b64 s[96:97], s[96:97], 15
	s_add_u32 s68, s29, s96
	s_addc_u32 s69, s30, s97
	s_xor_b32 s93, s92, 1
	s_mul_i32 s93, s93, 0x12400
	s_add_i32 s93, s93, 0
	v_add_u32_e32 v245, 0x400, v134
	v_add_u32_e32 v246, 0x800, v134
	v_add_u32_e32 v247, 0xc00, v134
	v_add_u32_e32 v248, 0x1000, v134
	s_lshl_b32 s32, s31, 4
	s_lshl_b32 s98, s31, 2
	s_add_i32 s98, s98, s32
	s_add_u32 s100, vcc_hi, s98
	s_addc_u32 s101, vcc_lo, 0
	s_add_i32 s99, s93, s98
	s_cmp_lg_u64 s[2:3], 0
	s_cbranch_scc1 .Lchain_nodec_0
	s_lshl_b64 s[22:23], s[22:23], 9
	s_add_i32 s98, s93, s31
	s_add_i32 m0, s98, 0x12000
	v_lshl_add_u64 v[250:251], v[156:157], 0, s[22:23]
	global_load_lds_dword v[250:251], off
.Lchain_nodec_0:
	s_add_i32 m0, s99, 0x0
	s_nop 0
	global_load_lds_dwordx4 v134, s[100:101] nt
	s_add_i32 m0, s99, 0x400
	s_nop 0
	global_load_lds_dwordx4 v245, s[100:101] nt
	s_add_i32 m0, s99, 0x800
	s_nop 0
	global_load_lds_dwordx4 v246, s[100:101] nt
	s_add_i32 m0, s99, 0xc00
	s_nop 0
	global_load_lds_dwordx4 v247, s[100:101] nt
	s_add_i32 m0, s99, 0x1000
	s_nop 0
	global_load_lds_dwordx4 v248, s[100:101] nt
	s_add_u32 s100, s68, s32
	s_addc_u32 s101, s69, 0
	s_add_i32 s99, s93, s32
	s_add_i32 m0, s99, 0xa000
	s_nop 0
	global_load_lds_dwordx4 v134, s[100:101] nt
	s_add_i32 m0, s99, 0xa400
	s_nop 0
	global_load_lds_dwordx4 v245, s[100:101] nt
	s_add_i32 m0, s99, 0xa800
	s_nop 0
	global_load_lds_dwordx4 v246, s[100:101] nt
	s_add_i32 m0, s99, 0xac00
	s_nop 0
	global_load_lds_dwordx4 v247, s[100:101] nt
	s_branch .LBB0_409
.Lchain_last_0:
	s_waitcnt vmcnt(16)
	s_branch .LBB0_409

; #define LAS __attribute__((address_space(3)))
; #define RD_QD(dst, s0) _Pragma("unroll") for (int s_ = 0; s_ < 4; ++s_) { dst[s_] = *(const LAS bf16x8*)(B + CH_QD + i0 * 256 + (((2 * ((s0) + s_) + hi) ^ (i0 & 15)) << 4)); \
;                 dst[4 + s_] = *(const LAS bf16x8*)(B + CH_QD + i1 * 256 + (((2 * ((s0) + s_) + hi) ^ (i1 & 15)) << 4)); }
; #define RD_KT(dst, db0) _Pragma("unroll") for (int q_ = 0; q_ < 2; ++q_) { const int d_ = ((db0) + q_) * 32 + r32; \
;                 _Pragma("unroll") for (int ks_ = 0; ks_ < 4; ++ks_) dst[q_ * 4 + ks_] = *(const LAS bf16x8*)(B + CH_KT + d_ * 128 + (((2 * ks_ + hi) ^ ((d_ >> 1) & 7)) << 4)); }
; #define DECAY(db_) do { f32x4 dc_[4]; _Pragma("unroll") for (int a4_ = 0; a4_ < 4; ++a4_) dc_[a4_] = *(const LAS f32x4*)(B + CH_DEC + ((db_) * 32 + 8 * a4_ + 4 * hi) * 4); \
;                 _Pragma("unroll") for (int a4_ = 0; a4_ < 4; ++a4_) _Pragma("unroll") for (int b4_ = 0; b4_ < 4; ++b4_) T[db_][a4_ * 4 + b4_] *= dc_[a4_][b4_]; } while (0)
; DI void phase_gla_chain(const Params& P, int l, int task0, int ntask_stride, LAS unsigned char* lds) {
;     ...
;             const int i0 = r32, i1 = 32 + r32; const int vv = wid * 32 + r32;
;             bf16x8 fa[8], fb[8], vf[4];
;             f32x16 o[2]; for (int x = 0; x < 16; ++x) { o[0][x] = 0.f; o[1][x] = 0.f; }
;     ...
;             RD_QD(fa, 0);
; #pragma unroll
;             for (int ks = 0; ks < 4; ++ks) vf[ks] = *(const LAS bf16x8*)(B + CH_VT + vv * 128 + (((2 * ks + hi) ^ ((vv >> 1) & 7)) << 4));
;             __builtin_amdgcn_sched_barrier(0);
;             RD_QD(fb, 4);
;             __builtin_amdgcn_sched_barrier(0);
;             MM_QD(fa, 0);
;             DECAY(0); DECAY(1);
;             __builtin_amdgcn_sched_barrier(0);
; #pragma unroll
;             for (int ks = 0; ks < 4; ++ks) { fa[ks] = *(const LAS bf16x8*)(B + CH_AM + i0 * 128 + (((2 * ks + hi) ^ ((i0 >> 1) & 7)) << 4)); fa[4 + ks] = *(const LAS bf16x8*)(B + CH_AM + i1 * 128 + (((2 * ks + hi) ^ ((i1 >> 1) & 7)) << 4)); }
;             __builtin_amdgcn_sched_barrier(0);
;             MM_QD(fb, 4);
;             DECAY(2); DECAY(3);
;             __builtin_amdgcn_sched_barrier(0);
;             RD_KT(fb, 0);
.LBB0_971:
	s_mul_i32 s84, s84, 0x12400
	s_add_i32 s22, s84, 0
	v_add_u32_e32 v74, s22, v201
	v_add_u32_e32 v75, s22, v141
	v_add_u32_e32 v66, v74, v149
	v_add_u32_e32 v70, v75, v149
	v_add_u32_e32 v76, v74, v151
	ds_read_b128 v[66:69], v66
	ds_read_b128 v[70:73], v70
	v_add_u32_e32 v77, v75, v151
	ds_read_b128 v[182:185], v76
	ds_read_b128 v[186:189], v77
	v_add_u32_e32 v76, v74, v153
	v_add_u32_e32 v77, v75, v153
	ds_read_b128 v[190:193], v76
	ds_read_b128 v[194:197], v77
	v_add_u32_e32 v76, v74, v160
	v_add_u32_e32 v77, v75, v160
	ds_read_b128 v[204:207], v76
	ds_read_b128 v[208:211], v77
	v_add_u32_e32 v76, v74, v167
	v_add_u32_e32 v77, v75, v167
	ds_read_b128 v[212:215], v76
	ds_read_b128 v[216:219], v77
	v_add_u32_e32 v76, v74, v168
	v_add_u32_e32 v77, v75, v168
	ds_read_b128 v[220:223], v76
	ds_read_b128 v[130:133], v77
	v_add_u32_e32 v76, v74, v169
	v_add_u32_e32 v74, v74, v170
	v_add_u32_e32 v77, v75, v169
	ds_read_b128 v[126:129], v76
	ds_read_b128 v[122:125], v77
	v_add_u32_e32 v75, v75, v170
	ds_read_b128 v[118:121], v74
	ds_read_b128 v[114:117], v75
	v_cvt_pk_bf16_f32 v74, v2, v3
	v_cvt_pk_bf16_f32 v75, v4, v5
	v_cvt_pk_bf16_f32 v76, v6, v7
	v_cvt_pk_bf16_f32 v77, v8, v9
	v_cvt_pk_bf16_f32 v224, v10, v11
	v_cvt_pk_bf16_f32 v225, v12, v13
	s_waitcnt lgkmcnt(0)
	v_mfma_f32_32x32x16_bf16 v[82:97], v[66:69], v[74:77], 0
	v_cvt_pk_bf16_f32 v226, v14, v15
	v_cvt_pk_bf16_f32 v227, v16, v17
	v_add_u32_e32 v198, s22, v146
	v_add_u32_e32 v199, 0x12000, v198
	v_cvt_pk_bf16_f32 v228, v26, v27
	v_cvt_pk_bf16_f32 v229, v28, v29
	v_cvt_pk_bf16_f32 v230, v30, v31
	v_mfma_f32_32x32x16_bf16 v[66:81], v[70:73], v[74:77], 0
	v_cvt_pk_bf16_f32 v231, v32, v33
	v_mfma_f32_32x32x16_bf16 v[82:97], v[182:185], v[224:227], v[82:97]
	v_cvt_pk_bf16_f32 v182, v18, v19
	v_cvt_pk_bf16_f32 v183, v20, v21
	v_cvt_pk_bf16_f32 v184, v22, v23
	v_cvt_pk_bf16_f32 v185, v24, v25
	v_mfma_f32_32x32x16_bf16 v[66:81], v[186:189], v[224:227], v[66:81]
	ds_read_b128 v[186:189], v199 offset:64
	ds_read_b128 v[224:227], v199 offset:96
	ds_read_b128 v[232:235], v199
	ds_read_b128 v[236:239], v199 offset:32
	s_waitcnt lgkmcnt(0)
	v_pk_mul_f32 v[10:11], v[10:11], v[186:187]
	v_pk_mul_f32 v[12:13], v[12:13], v[188:189]
	v_pk_mul_f32 v[14:15], v[14:15], v[224:225]
	v_pk_mul_f32 v[6:7], v[6:7], v[236:237]
	v_pk_mul_f32 v[16:17], v[16:17], v[226:227]
	v_mfma_f32_32x32x16_bf16 v[82:97], v[190:193], v[182:185], v[82:97]
	v_mul_f32_e64 v8, v8, v238
	v_mul_f32_e64 v9, v9, v239
	v_mul_f32_e64 v4, v4, v234
	v_mul_f32_e64 v5, v5, v235
	v_mul_f32_e64 v2, v2, v232
	v_mul_f32_e64 v3, v3, v233
	v_mfma_f32_32x32x16_bf16 v[66:81], v[194:197], v[182:185], v[66:81]
	v_add_u32_e32 v194, 0x12080, v198
	ds_read_b128 v[182:185], v194 offset:64
	ds_read_b128 v[186:189], v194 offset:96
	ds_read_b128 v[190:193], v194
	ds_read_b128 v[194:197], v194 offset:32
	s_waitcnt lgkmcnt(0)
	v_pk_mul_f32 v[26:27], v[26:27], v[182:183]
	v_pk_mul_f32 v[30:31], v[30:31], v[186:187]
	v_pk_mul_f32 v[32:33], v[32:33], v[188:189]
	v_pk_mul_f32 v[22:23], v[22:23], v[194:195]
	v_pk_mul_f32 v[28:29], v[28:29], v[184:185]
	v_pk_mul_f32 v[24:25], v[24:25], v[196:197]
	v_pk_mul_f32 v[20:21], v[20:21], v[192:193]
	v_pk_mul_f32 v[18:19], v[18:19], v[190:191]
	v_mfma_f32_32x32x16_bf16 v[82:97], v[204:207], v[228:231], v[82:97]
	v_mfma_f32_32x32x16_bf16 v[66:81], v[208:211], v[228:231], v[66:81]
	v_add_u32_e32 v199, s22, v143
	v_add_u32_e32 v224, s22, v145
	v_add_u32_e32 v240, v199, v162
	v_add_u32_e32 v186, v224, v162
	v_add_u32_e32 v241, v199, v164
	v_add_u32_e32 v194, v224, v164
	v_add_u32_e32 v242, v199, v165
	v_add_u32_e32 v208, v224, v165
	v_add_u32_e32 v199, v199, v166
	v_add_u32_e32 v228, v224, v166
	ds_read_b128 v[182:185], v240 offset:16384
	ds_read_b128 v[186:189], v186 offset:16384
	ds_read_b128 v[190:193], v241 offset:16384
	ds_read_b128 v[194:197], v194 offset:16384
	ds_read_b128 v[204:207], v242 offset:16384
	ds_read_b128 v[208:211], v208 offset:16384
	ds_read_b128 v[224:227], v199 offset:16384
	ds_read_b128 v[228:231], v228 offset:16384
	v_cvt_pk_bf16_f32 v232, v34, v35
	v_cvt_pk_bf16_f32 v233, v36, v37
	v_cvt_pk_bf16_f32 v234, v38, v39
	v_cvt_pk_bf16_f32 v235, v40, v41
	s_nop 1
	v_mfma_f32_32x32x16_bf16 v[82:97], v[212:215], v[232:235], v[82:97]
	v_cvt_pk_bf16_f32 v212, v42, v43
	v_cvt_pk_bf16_f32 v213, v44, v45
	v_cvt_pk_bf16_f32 v214, v46, v47
	v_cvt_pk_bf16_f32 v215, v48, v49
	v_mfma_f32_32x32x16_bf16 v[66:81], v[216:219], v[232:235], v[66:81]
	v_cvt_pk_bf16_f32 v216, v50, v51
	v_cvt_pk_bf16_f32 v217, v52, v53
	v_cvt_pk_bf16_f32 v218, v54, v55
	v_cvt_pk_bf16_f32 v219, v56, v57
	v_mfma_f32_32x32x16_bf16 v[82:97], v[220:223], v[212:215], v[82:97]
	v_add_u32_e32 v223, 0x12100, v198
	v_add_u32_e32 v198, 0x12180, v198
	v_cvt_pk_bf16_f32 v220, v58, v59
	v_cvt_pk_bf16_f32 v221, v60, v61
	v_cvt_pk_bf16_f32 v222, v62, v63
	v_mfma_f32_32x32x16_bf16 v[66:81], v[130:133], v[212:215], v[66:81]
	ds_read_b128 v[130:133], v223 offset:64
	ds_read_b128 v[212:215], v223 offset:96
	ds_read_b128 v[232:235], v223
	ds_read_b128 v[236:239], v223 offset:32
	v_cvt_pk_bf16_f32 v223, v64, v65
	s_waitcnt lgkmcnt(0)
	v_pk_mul_f32 v[42:43], v[42:43], v[130:131]
	v_pk_mul_f32 v[46:47], v[46:47], v[212:213]
	v_pk_mul_f32 v[48:49], v[48:49], v[214:215]
	v_pk_mul_f32 v[44:45], v[44:45], v[132:133]
	v_pk_mul_f32 v[38:39], v[38:39], v[236:237]
	v_mfma_f32_32x32x16_bf16 v[82:97], v[126:129], v[216:219], v[82:97]
	v_mul_f32_e64 v40, v40, v238
	v_mul_f32_e64 v41, v41, v239
	v_mul_f32_e64 v36, v36, v234
	v_mul_f32_e64 v37, v37, v235
	v_mul_f32_e64 v34, v34, v232
	v_mul_f32_e64 v35, v35, v233
	v_mfma_f32_32x32x16_bf16 v[66:81], v[122:125], v[216:219], v[66:81]
	ds_read_b128 v[122:125], v198 offset:64
	ds_read_b128 v[126:129], v198 offset:96
	ds_read_b128 v[130:133], v198
	ds_read_b128 v[212:215], v198 offset:32
	s_waitcnt lgkmcnt(0)
	v_pk_mul_f32 v[58:59], v[58:59], v[122:123]
	v_pk_mul_f32 v[62:63], v[62:63], v[126:127]
	v_pk_mul_f32 v[64:65], v[64:65], v[128:129]
	v_pk_mul_f32 v[54:55], v[54:55], v[212:213]
	v_pk_mul_f32 v[60:61], v[60:61], v[124:125]
	v_pk_mul_f32 v[56:57], v[56:57], v[214:215]
	v_pk_mul_f32 v[52:53], v[52:53], v[132:133]
	v_pk_mul_f32 v[50:51], v[50:51], v[130:131]
	v_mfma_f32_32x32x16_bf16 v[82:97], v[118:121], v[220:223], v[82:97]
	v_mfma_f32_32x32x16_bf16 v[66:81], v[114:117], v[220:223], v[66:81]
	ds_read_b128 v[114:117], v240 offset:24576
	ds_read_b128 v[118:121], v240 offset:28672
	ds_read_b128 v[122:125], v241 offset:24576
	ds_read_b128 v[126:129], v241 offset:28672
	ds_read_b128 v[130:133], v242 offset:24576
	ds_read_b128 v[212:215], v242 offset:28672
	ds_read_b128 v[216:219], v199 offset:24576
	ds_read_b128 v[220:223], v199 offset:28672
	s_waitcnt vmcnt(25)
	s_barrier
; #define LAS __attribute__((address_space(3)))
; DI int crow(int r, int hi) { return (r & 3) + 8 * (r >> 2) + 4 * hi; }
; DI void phase_gla_chain(const Params& P, int l, int task0, int ntask_stride, LAS unsigned char* lds) {
;     ...
;             for (int ks = 0; ks < 4; ++ks) vf[ks] = *(const LAS bf16x8*)(B + CH_VT + vv * 128 + (((2 * ks + hi) ^ ((vv >> 1) & 7)) << 4));
;             __builtin_amdgcn_sched_barrier(0);
;             RD_QD(fb, 4);
;             __builtin_amdgcn_sched_barrier(0);
;             MM_QD(fa, 0);
;             DECAY(0); DECAY(1);
;             __builtin_amdgcn_sched_barrier(0);
; #pragma unroll
;             for (int ks = 0; ks < 4; ++ks) { fa[ks] = *(const LAS bf16x8*)(B + CH_AM + i0 * 128 + (((2 * ks + hi) ^ ((i0 >> 1) & 7)) << 4)); fa[4 + ks] = *(const LAS bf16x8*)(B + CH_AM + i1 * 128 + (((2 * ks + hi) ^ ((i1 >> 1) & 7)) << 4)); }
;             __builtin_amdgcn_sched_barrier(0);
;             MM_QD(fb, 4);
;             DECAY(2); DECAY(3);
;             __builtin_amdgcn_sched_barrier(0);
;             RD_KT(fb, 0);
;             __builtin_amdgcn_sched_barrier(0);
; #pragma unroll
;             for (int ks = 0; ks < 4; ++ks) { o[0] = __builtin_amdgcn_mfma_f32_32x32x16_bf16(fa[ks], vf[ks], o[0], 0, 0, 0); o[1] = __builtin_amdgcn_mfma_f32_32x32x16_bf16(fa[4 + ks], vf[ks], o[1], 0, 0, 0); }
;             __builtin_amdgcn_sched_barrier(0);
;             RD_KT(fa, 2);
;             __builtin_amdgcn_sched_barrier(0);
;             MM_KT(fb, 0);
;             __builtin_amdgcn_sched_barrier(0);
;             MM_KT(fa, 2);
;     ...
;             { const int cs = dir ? 63 - n : n; const size_t tokb = (size_t)sq * SEQL + cs * 64; const int odd = lane & 1;
;               bf16_t* ob = OFB + (size_t)dir * MTOK * 1024 + h * 256 + wid * 32 + (r32 & ~1);
; #pragma unroll
;               for (int ib = 0; ib < 2; ++ib)
; #pragma unroll
;                   for (int x = 0; x < 16; x += 2) { float ea_ = o[ib][x], eb_ = o[ib][x + 1]; asm volatile("" : "+v"(ea_), "+v"(eb_)); const float mine = odd ? eb_ : ea_, give = odd ? ea_ : eb_;
;                       const float got = __int_as_float(__builtin_amdgcn_update_dpp(0, __float_as_int(give), 0xB1, 0xF, 0xF, true));
;                       const unsigned w = odd ? pkbf(got, mine) : pkbf(mine, got);
;                       *(unsigned*)(ob + (tokb + ib * 32 + crow(x + odd, hi)) * 1024) = w; } }
	v_add_u32_e32 v249, s22, v173
	v_add_u32_e32 v250, v249, v162
	v_add_u32_e32 v251, v249, v164
	ds_read_b128 v[110:113], v250 offset:40960
	ds_read_b128 v[106:109], v251 offset:40960
	v_add_u32_e32 v250, v249, v165
	v_add_u32_e32 v249, v249, v166
	ds_read_b128 v[102:105], v250 offset:40960
	ds_read_b128 v[98:101], v249 offset:40960
	s_waitcnt lgkmcnt(0)
	v_mfma_f32_32x32x16_bf16 v[82:97], v[182:185], v[110:113], v[82:97]
	v_mfma_f32_32x32x16_bf16 v[66:81], v[186:189], v[110:113], v[66:81]
	v_mfma_f32_32x32x16_bf16 v[82:97], v[190:193], v[106:109], v[82:97]
	v_mfma_f32_32x32x16_bf16 v[66:81], v[194:197], v[106:109], v[66:81]
	v_mfma_f32_32x32x16_bf16 v[82:97], v[204:207], v[102:105], v[82:97]
	v_mfma_f32_32x32x16_bf16 v[66:81], v[208:211], v[102:105], v[66:81]
	v_mfma_f32_32x32x16_bf16 v[82:97], v[224:227], v[98:101], v[82:97]
	v_mfma_f32_32x32x16_bf16 v[66:81], v[228:231], v[98:101], v[66:81]
	ds_read_b128 v[182:185], v240 offset:32768
	ds_read_b128 v[186:189], v240 offset:36864
	ds_read_b128 v[190:193], v241 offset:32768
	ds_read_b128 v[194:197], v241 offset:36864
	ds_read_b128 v[204:207], v242 offset:32768
	ds_read_b128 v[208:211], v242 offset:36864
	ds_read_b128 v[224:227], v199 offset:32768
	ds_read_b128 v[228:231], v199 offset:36864
	s_waitcnt lgkmcnt(0)
	v_mfma_f32_32x32x16_bf16 v[2:17], v[114:117], v[110:113], v[2:17]
	v_mfma_f32_32x32x16_bf16 v[18:33], v[118:121], v[110:113], v[18:33]
	v_mfma_f32_32x32x16_bf16 v[2:17], v[122:125], v[106:109], v[2:17]
	v_mfma_f32_32x32x16_bf16 v[18:33], v[126:129], v[106:109], v[18:33]
	v_mfma_f32_32x32x16_bf16 v[2:17], v[130:133], v[102:105], v[2:17]
	v_mfma_f32_32x32x16_bf16 v[18:33], v[212:215], v[102:105], v[18:33]
	v_mfma_f32_32x32x16_bf16 v[2:17], v[216:219], v[98:101], v[2:17]
	v_mfma_f32_32x32x16_bf16 v[18:33], v[220:223], v[98:101], v[18:33]
	s_add_i32 s64, s8, 1
	s_and_b64 s[22:23], s[10:11], exec
	s_cselect_b32 s22, s83, s64
	s_lshl_b32 s22, s22, 6
	s_add_u32 s23, s20, s22
	v_cndmask_b32_e64 v114, v82, v83, s[0:1]
	s_addc_u32 s22, s21, 0
	v_mfma_f32_32x32x16_bf16 v[34:49], v[182:185], v[110:113], v[34:49]
	v_mov_b32_dpp v114, v114 quad_perm:[1,0,3,2] row_mask:0xf bank_mask:0xf bound_ctrl:1
	v_cndmask_b32_e64 v83, v83, v114, s[0:1]
	v_cndmask_b32_e64 v82, v114, v82, s[0:1]
	v_cvt_pk_bf16_f32 v114, v82, v83
	v_readfirstlane_b32 s98, v158
	v_readfirstlane_b32 s99, v159
	v_and_b32_e32 v244, 30, v137
	v_lshlrev_b32_e32 v244, 1, v244
	v_lshl_add_u32 v244, v136, 11, v244
	s_lshl_b32 s100, s23, 11
	s_add_u32 s98, s98, s100
	s_addc_u32 s99, s99, 0
	s_add_u32 s100, s98, 0x800
	s_addc_u32 s101, s99, 0
	global_store_dword v244, v114, s[100:101] offset:-2048
	v_mov_b32_e32 v82, v84
	v_mfma_f32_32x32x16_bf16 v[50:65], v[186:189], v[110:113], v[50:65]
	v_cndmask_b32_e64 v83, v82, v85, s[0:1]
	s_add_i32 s8, s8, -1
	s_add_i32 s82, s82, 1
	v_mov_b32_dpp v83, v83 quad_perm:[1,0,3,2] row_mask:0xf bank_mask:0xf bound_ctrl:1
	v_cndmask_b32_e64 v84, v85, v83, s[0:1]
	v_cndmask_b32_e64 v82, v83, v82, s[0:1]
	v_cvt_pk_bf16_f32 v84, v82, v84
	global_store_dword v244, v84, s[100:101] offset:2048
	v_mov_b32_e32 v82, v86
	v_mfma_f32_32x32x16_bf16 v[34:49], v[190:193], v[106:109], v[34:49]
	v_cndmask_b32_e64 v83, v82, v87, s[0:1]
	s_nop 1
	v_mov_b32_dpp v83, v83 quad_perm:[1,0,3,2] row_mask:0xf bank_mask:0xf bound_ctrl:1
	v_cndmask_b32_e64 v84, v87, v83, s[0:1]
	v_cndmask_b32_e64 v82, v83, v82, s[0:1]
	v_cvt_pk_bf16_f32 v84, v82, v84
	s_add_u32 s100, s98, 0x4800
	s_addc_u32 s101, s99, 0
	global_store_dword v244, v84, s[100:101] offset:-2048
	v_mov_b32_e32 v82, v89
	v_mfma_f32_32x32x16_bf16 v[50:65], v[194:197], v[106:109], v[50:65]
	v_cndmask_b32_e64 v83, v88, v82, s[0:1]
	s_nop 1
	v_mov_b32_dpp v83, v83 quad_perm:[1,0,3,2] row_mask:0xf bank_mask:0xf bound_ctrl:1
	v_cndmask_b32_e64 v82, v82, v83, s[0:1]
	v_cndmask_b32_e64 v83, v83, v88, s[0:1]
	v_cvt_pk_bf16_f32 v84, v83, v82
	global_store_dword v244, v84, s[100:101] offset:2048
	v_mov_b32_e32 v82, v90
	v_mfma_f32_32x32x16_bf16 v[34:49], v[204:207], v[102:105], v[34:49]
	v_cndmask_b32_e64 v83, v82, v91, s[0:1]
	s_nop 1
	v_mov_b32_dpp v83, v83 quad_perm:[1,0,3,2] row_mask:0xf bank_mask:0xf bound_ctrl:1
	v_cndmask_b32_e64 v84, v91, v83, s[0:1]
	v_cndmask_b32_e64 v82, v83, v82, s[0:1]
	v_cvt_pk_bf16_f32 v84, v82, v84
	s_add_u32 s100, s98, 0x8800
	s_addc_u32 s101, s99, 0
	global_store_dword v244, v84, s[100:101] offset:-2048
	v_mov_b32_e32 v82, v92
	v_mfma_f32_32x32x16_bf16 v[50:65], v[208:211], v[102:105], v[50:65]
	v_cndmask_b32_e64 v83, v82, v93, s[0:1]
	s_nop 1
	v_mov_b32_dpp v83, v83 quad_perm:[1,0,3,2] row_mask:0xf bank_mask:0xf bound_ctrl:1
	v_cndmask_b32_e64 v84, v93, v83, s[0:1]
	v_cndmask_b32_e64 v82, v83, v82, s[0:1]
	v_cvt_pk_bf16_f32 v84, v82, v84
	global_store_dword v244, v84, s[100:101] offset:2048
	v_mov_b32_e32 v82, v95
	v_mfma_f32_32x32x16_bf16 v[34:49], v[224:227], v[98:101], v[34:49]
	v_cndmask_b32_e64 v83, v94, v82, s[0:1]
	s_nop 1
	v_mov_b32_dpp v83, v83 quad_perm:[1,0,3,2] row_mask:0xf bank_mask:0xf bound_ctrl:1
	v_cndmask_b32_e64 v82, v82, v83, s[0:1]
	v_cndmask_b32_e64 v83, v83, v94, s[0:1]
	v_cvt_pk_bf16_f32 v84, v83, v82
	s_add_u32 s100, s98, 0xc800
	s_addc_u32 s101, s99, 0
	global_store_dword v244, v84, s[100:101] offset:-2048
	v_mov_b32_e32 v82, v96
	v_mfma_f32_32x32x16_bf16 v[50:65], v[228:231], v[98:101], v[50:65]
	v_cndmask_b32_e64 v83, v82, v97, s[0:1]
; DI int crow(int r, int hi) { return (r & 3) + 8 * (r >> 2) + 4 * hi; }
; DI unsigned pkbf(float a, float b) { f32x2 v = {a, b}; bfx2 r = __builtin_convertvector(v, bfx2); return __builtin_bit_cast(unsigned, r); }
; DI void phase_gla_chain(const Params& P, int l, int task0, int ntask_stride, LAS unsigned char* lds) {
;     ...
;         __syncthreads();
;         CH_ISSUE(0, 0);
;         for (int n = 0; n < 64; ++n) {
;             const int b = n & 1;
;             if (n == 0) asm volatile("s_waitcnt vmcnt(0)" ::: "memory"); else asm volatile("s_waitcnt vmcnt(16)" ::: "memory");
;             __builtin_amdgcn_s_barrier();
;             asm volatile("" ::: "memory");
;             if (n + 1 < 64) CH_ISSUE(n + 1, b ^ 1);
;     ...
;             { const int cs = dir ? 63 - n : n; const size_t tokb = (size_t)sq * SEQL + cs * 64; const int odd = lane & 1;
;               bf16_t* ob = OFB + (size_t)dir * MTOK * 1024 + h * 256 + wid * 32 + (r32 & ~1);
; #pragma unroll
;               for (int ib = 0; ib < 2; ++ib)
; #pragma unroll
;                   for (int x = 0; x < 16; x += 2) { float ea_ = o[ib][x], eb_ = o[ib][x + 1]; asm volatile("" : "+v"(ea_), "+v"(eb_)); const float mine = odd ? eb_ : ea_, give = odd ? ea_ : eb_;
;                       const float got = __int_as_float(__builtin_amdgcn_update_dpp(0, __float_as_int(give), 0xB1, 0xF, 0xF, true));
;                       const unsigned w = odd ? pkbf(got, mine) : pkbf(mine, got);
;                       *(unsigned*)(ob + (tokb + ib * 32 + crow(x + odd, hi)) * 1024) = w; } }
	s_nop 1
	v_mov_b32_dpp v83, v83 quad_perm:[1,0,3,2] row_mask:0xf bank_mask:0xf bound_ctrl:1
	v_cndmask_b32_e64 v84, v97, v83, s[0:1]
	v_cndmask_b32_e64 v82, v83, v82, s[0:1]
	v_cvt_pk_bf16_f32 v84, v82, v84
	global_store_dword v244, v84, s[100:101] offset:2048
	s_or_b32 s23, s23, 32
	v_cndmask_b32_e64 v82, v66, v67, s[0:1]
	s_nop 0
	v_mov_b32_dpp v82, v82 quad_perm:[1,0,3,2] row_mask:0xf bank_mask:0xf bound_ctrl:1
	v_cndmask_b32_e64 v67, v67, v82, s[0:1]
	v_cndmask_b32_e64 v66, v82, v66, s[0:1]
	v_cvt_pk_bf16_f32 v82, v66, v67
	s_add_u32 s100, s98, 0x10800
	s_addc_u32 s101, s99, 0
	global_store_dword v244, v82, s[100:101] offset:-2048
	v_mov_b32_e32 v66, v69
	s_nop 0
	v_cndmask_b32_e64 v67, v68, v66, s[0:1]
	s_nop 1
	v_mov_b32_dpp v67, v67 quad_perm:[1,0,3,2] row_mask:0xf bank_mask:0xf bound_ctrl:1
	v_cndmask_b32_e64 v66, v66, v67, s[0:1]
	v_cndmask_b32_e64 v67, v67, v68, s[0:1]
	v_cvt_pk_bf16_f32 v68, v67, v66
	global_store_dword v244, v68, s[100:101] offset:2048
	v_mov_b32_e32 v66, v70
	s_nop 0
	v_cndmask_b32_e64 v67, v66, v71, s[0:1]
	s_nop 1
	v_mov_b32_dpp v67, v67 quad_perm:[1,0,3,2] row_mask:0xf bank_mask:0xf bound_ctrl:1
	v_cndmask_b32_e64 v68, v71, v67, s[0:1]
	v_cndmask_b32_e64 v66, v67, v66, s[0:1]
	v_cvt_pk_bf16_f32 v68, v66, v68
	s_add_u32 s100, s98, 0x14800
	s_addc_u32 s101, s99, 0
	global_store_dword v244, v68, s[100:101] offset:-2048
	v_mov_b32_e32 v66, v72
	s_nop 0
	v_cndmask_b32_e64 v67, v66, v73, s[0:1]
	s_nop 1
	v_mov_b32_dpp v67, v67 quad_perm:[1,0,3,2] row_mask:0xf bank_mask:0xf bound_ctrl:1
	v_cndmask_b32_e64 v68, v73, v67, s[0:1]
	v_cndmask_b32_e64 v66, v67, v66, s[0:1]
	v_cvt_pk_bf16_f32 v68, v66, v68
	global_store_dword v244, v68, s[100:101] offset:2048
	v_mov_b32_e32 v66, v75
	s_nop 0
	v_cndmask_b32_e64 v67, v74, v66, s[0:1]
	s_nop 1
	v_mov_b32_dpp v67, v67 quad_perm:[1,0,3,2] row_mask:0xf bank_mask:0xf bound_ctrl:1
	v_cndmask_b32_e64 v66, v66, v67, s[0:1]
	v_cndmask_b32_e64 v67, v67, v74, s[0:1]
	v_cvt_pk_bf16_f32 v68, v67, v66
	s_add_u32 s100, s98, 0x18800
	s_addc_u32 s101, s99, 0
	global_store_dword v244, v68, s[100:101] offset:-2048
	v_mov_b32_e32 v66, v77
	s_nop 0
	v_cndmask_b32_e64 v67, v76, v66, s[0:1]
	s_nop 1
	v_mov_b32_dpp v67, v67 quad_perm:[1,0,3,2] row_mask:0xf bank_mask:0xf bound_ctrl:1
	v_cndmask_b32_e64 v66, v66, v67, s[0:1]
	v_cndmask_b32_e64 v67, v67, v76, s[0:1]
	v_cvt_pk_bf16_f32 v68, v67, v66
	global_store_dword v244, v68, s[100:101] offset:2048
	v_mov_b32_e32 v66, v78
	s_nop 0
	v_cndmask_b32_e64 v67, v66, v79, s[0:1]
	s_nop 1
	v_mov_b32_dpp v67, v67 quad_perm:[1,0,3,2] row_mask:0xf bank_mask:0xf bound_ctrl:1
	v_cndmask_b32_e64 v68, v79, v67, s[0:1]
	v_cndmask_b32_e64 v66, v67, v66, s[0:1]
	v_cvt_pk_bf16_f32 v68, v66, v68
	s_add_u32 s100, s98, 0x1c800
	s_addc_u32 s101, s99, 0
	global_store_dword v244, v68, s[100:101] offset:-2048
	v_mov_b32_e32 v66, v81
	s_nop 0
	v_cndmask_b32_e64 v67, v80, v66, s[0:1]
	s_nop 1
	v_mov_b32_dpp v67, v67 quad_perm:[1,0,3,2] row_mask:0xf bank_mask:0xf bound_ctrl:1
	v_cndmask_b32_e64 v66, v66, v67, s[0:1]
	v_cndmask_b32_e64 v67, v67, v80, s[0:1]
	v_cvt_pk_bf16_f32 v68, v67, v66
	global_store_dword v244, v68, s[100:101] offset:2048
	s_cmp_eq_u32 s8, -2
	s_cbranch_scc1 .LBB0_965
.LBB0_972:
	s_add_i32 s83, s82, -1
	s_cmp_lg_u32 s83, 1
	s_cbranch_scc1 .Lchain_w_1
	s_waitcnt vmcnt(16)
.Lchain_w_1:
	s_waitcnt vmcnt(20)
	s_barrier
	s_and_b32 s84, s83, 1
	s_cmp_eq_u32 s8, -1
	s_cbranch_scc1 .Lchain_last_1
	s_and_b64 s[22:23], s[10:11], exec
	s_cselect_b32 s22, s82, s8
	s_add_i32 s22, s22, s81
	s_lshl_b32 s22, s22, 2
	s_or_b32 s86, s22, s80
	s_ashr_i32 s87, s86, 31
	s_add_u32 s22, s25, s86
	s_addc_u32 s23, 0, s87
	s_mul_i32 s64, s23, 0xa000
	s_mul_hi_u32 s65, s22, 0xa000
	s_add_i32 s65, s65, s64
	s_mul_i32 s64, s22, 0xa000
	s_add_u32 s64, s27, s64
	s_addc_u32 s65, s28, s65
	s_lshl_b64 s[86:87], s[86:87], 15
	s_add_u32 s66, s29, s86
	s_addc_u32 s67, s30, s87
	s_xor_b32 s68, s84, 1
	s_mul_i32 s68, s68, 0x12400
	s_add_i32 s85, s68, 0
	v_add_u32_e32 v245, 0x400, v134
	v_add_u32_e32 v246, 0x800, v134
	v_add_u32_e32 v247, 0xc00, v134
	v_add_u32_e32 v248, 0x1000, v134
	s_lshl_b32 s32, s31, 4
	s_lshl_b32 s98, s31, 2
	s_add_i32 s98, s98, s32
	s_add_u32 s100, s64, s98
	s_addc_u32 s101, s65, 0
	s_add_i32 s99, s85, s98
	s_cmp_lg_u64 s[2:3], 0
	s_cbranch_scc1 .Lchain_nodec_1
	s_lshl_b64 s[22:23], s[22:23], 9
	s_add_i32 s98, s85, s31
	s_add_i32 m0, s98, 0x12000
	v_lshl_add_u64 v[250:251], v[156:157], 0, s[22:23]
	global_load_lds_dword v[250:251], off
.Lchain_nodec_1:
	s_add_i32 m0, s99, 0x0
	s_nop 0
	global_load_lds_dwordx4 v134, s[100:101] nt
	s_add_i32 m0, s99, 0x400
	s_nop 0
	global_load_lds_dwordx4 v245, s[100:101] nt
	s_add_i32 m0, s99, 0x800
	s_nop 0
	global_load_lds_dwordx4 v246, s[100:101] nt
	s_add_i32 m0, s99, 0xc00
	s_nop 0
	global_load_lds_dwordx4 v247, s[100:101] nt
	s_add_i32 m0, s99, 0x1000
	s_nop 0
	global_load_lds_dwordx4 v248, s[100:101] nt
	s_add_u32 s100, s66, s32
	s_addc_u32 s101, s67, 0
	s_add_i32 s99, s85, s32
	s_add_i32 m0, s99, 0xa000
	s_nop 0
	global_load_lds_dwordx4 v134, s[100:101] nt
	s_add_i32 m0, s99, 0xa400
	s_nop 0
	global_load_lds_dwordx4 v245, s[100:101] nt
	s_add_i32 m0, s99, 0xa800
	s_nop 0
	global_load_lds_dwordx4 v246, s[100:101] nt
	s_add_i32 m0, s99, 0xac00
	s_nop 0
	global_load_lds_dwordx4 v247, s[100:101] nt
	s_branch .LBB0_971
